# diff-attention loops: row-sum packed-add chains de-serialised (two interleaved chains, hazard pads no longer needed); plus earlier nop/wait trims
# speedup vs baseline: 1.0193x; 1.0046x over previous
; __device__ __forceinline__ unsigned cvtpk(float lo, float hi) { const f32x2 v = {lo, hi}; const bf16x2_t b = __builtin_convertvector(v, bf16x2_t); return __builtin_bit_cast(unsigned, b); }
; #define MFMA32(a, b, c) __builtin_amdgcn_mfma_f32_32x32x16_bf16((a), (b), (c), 0, 0, 0)
; #define PV_IDX(g) (((g) & 1) * 4 + PV_KS(g))
; template <int DQK, int DV, bool MLA>
; __device__ __forceinline__ void attn_pass(LAS unsigned char* lds, const bf16_t* Qrow, const bf16_t* K0, int pitchK, const bf16_t* KrB, const bf16_t* Vt0, int NT, int q0w,
;                                           f32x16 (&o)[DV / 32], float& l_out, int tid) {
;     ...
;             if (pend) {
; #pragma unroll
;                 for (int g = 0; g <= NG; ++g) {
;                     if (g < NG) {
;                         o[PV_D(g)] = MFMA32(vf[PV_IDX(g)], pf[PV_KS(g)], o[PV_D(g)]);
;                         if (NDV == 4 && g < 8) vf[PV_IDX(g)] = VFRAG(vp, PV_D(g) + 2, PV_KS(g));
; #pragma unroll
;                         for (int e = g * EPG; e < (g + 1) * EPG; ++e) { if (e < 16) s0[e] = __builtin_amdgcn_exp2f(MLA ? s0[e] : s0[e] - m); else s1[e - 16] = __builtin_amdgcn_exp2f(MLA ? s1[e - 16] : s1[e - 16] - m); }
;                     }
;                     if (g > 0) {
; #pragma unroll
;                         for (int e = (g - 1) * EPG; e < g * EPG; ++e) {
;                             const float v = e < 16 ? s0[e] : s1[e - 16];
;                             if (e & 1) ps1 += v; else ps += v;
;                             if (e & 1) { const int j = e >> 1; pw[j >> 2][j & 3] = e < 16 ? cvtpk(s0[e - 1], s0[e]) : cvtpk(s1[e - 17], s1[e - 16]); }
;                         }
;                     }
;                     __builtin_amdgcn_sched_barrier(0);
;                 }
.LBB0_122:
	s_or_saveexec_b64 s[6:7], s[6:7]
	v_mov_b32_e32 v207, 0
	s_xor_b64 exec, exec, s[6:7]
	s_cbranch_execz .LBB0_124
	s_waitcnt lgkmcnt(7)
	v_mfma_f32_32x32x16_bf16 v[66:81], v[170:173], v[34:37], v[66:81]
	v_sub_f32_e32 v98, v98, v244
	ds_read_b128 v[170:173], v246 offset:40960
	v_exp_f32_e32 v206, v98
	v_sub_f32_e32 v98, v99, v244
	v_exp_f32_e32 v207, v98
	s_waitcnt lgkmcnt(7)
	v_mfma_f32_32x32x16_bf16 v[50:65], v[162:165], v[34:37], v[50:65]
	ds_read_b128 v[162:165], v246 offset:45056
	v_sub_f32_e32 v98, v100, v244
	v_exp_f32_e32 v246, v98
	v_sub_f32_e32 v98, v101, v244
	v_exp_f32_e32 v247, v98
	v_cvt_pk_bf16_f32 v98, v206, v207
	s_waitcnt lgkmcnt(7)
	v_mfma_f32_32x32x16_bf16 v[66:81], v[178:181], v[38:41], v[66:81]
	ds_read_b128 v[178:181], v245 offset:40960
	v_sub_f32_e32 v99, v102, v244
	v_exp_f32_e32 v102, v99
	v_sub_f32_e32 v99, v103, v244
	v_exp_f32_e32 v103, v99
	v_cvt_pk_bf16_f32 v99, v246, v247
	s_waitcnt lgkmcnt(7)
	v_mfma_f32_32x32x16_bf16 v[50:65], v[166:169], v[38:41], v[50:65]
	ds_read_b128 v[166:169], v245 offset:45056
	v_sub_f32_e32 v100, v104, v244
	v_exp_f32_e32 v104, v100
	v_sub_f32_e32 v100, v105, v244
	v_exp_f32_e32 v105, v100
	v_cvt_pk_bf16_f32 v100, v102, v103
	s_waitcnt lgkmcnt(7)
	v_mfma_f32_32x32x16_bf16 v[66:81], v[186:189], v[42:45], v[66:81]
	ds_read_b128 v[186:189], v222 offset:40960
	v_sub_f32_e32 v101, v106, v244
	v_exp_f32_e32 v106, v101
	v_sub_f32_e32 v101, v107, v244
	v_exp_f32_e32 v107, v101
	v_cvt_pk_bf16_f32 v101, v104, v105
	s_waitcnt lgkmcnt(7)
	v_mfma_f32_32x32x16_bf16 v[50:65], v[174:177], v[42:45], v[50:65]
	v_pk_add_f32 v[102:103], v[104:105], v[102:103]
	v_sub_f32_e32 v108, v108, v244
	v_exp_f32_e32 v248, v108
	v_sub_f32_e32 v108, v109, v244
	ds_read_b128 v[174:177], v222 offset:45056
	v_exp_f32_e32 v249, v108
	v_pk_add_f32 v[102:103], v[106:107], v[102:103]
	v_pk_add_f32 v[108:109], v[246:247], v[206:207]
	s_nop 0
	v_pk_add_f32 v[206:207], v[102:103], v[108:109]
	v_cvt_pk_bf16_f32 v102, v106, v107
	s_waitcnt lgkmcnt(7)
	v_mfma_f32_32x32x16_bf16 v[66:81], v[190:193], v[46:49], v[66:81]
	ds_read_b128 v[190:193], v221 offset:40960
	v_sub_f32_e32 v103, v110, v244
	v_exp_f32_e32 v246, v103
	v_sub_f32_e32 v103, v111, v244
	v_exp_f32_e32 v247, v103
	v_cvt_pk_bf16_f32 v103, v248, v249
	s_waitcnt lgkmcnt(7)
	v_mfma_f32_32x32x16_bf16 v[50:65], v[182:185], v[46:49], v[50:65]
	ds_read_b128 v[182:185], v221 offset:45056
	v_sub_f32_e32 v104, v112, v244
	v_exp_f32_e32 v112, v104
	v_sub_f32_e32 v104, v113, v244
	v_exp_f32_e32 v113, v104
	v_cvt_pk_bf16_f32 v104, v246, v247
	s_waitcnt lgkmcnt(7)
	v_mfma_f32_32x32x16_bf16 v[18:33], v[170:173], v[34:37], v[18:33]
	v_sub_f32_e32 v82, v82, v244
	v_sub_f32_e32 v83, v83, v244
	v_exp_f32_e32 v82, v82
	v_exp_f32_e32 v83, v83
	v_cvt_pk_bf16_f32 v105, v112, v113
	s_waitcnt lgkmcnt(6)
	v_mfma_f32_32x32x16_bf16 v[2:17], v[162:165], v[34:37], v[2:17]
	v_sub_f32_e32 v34, v84, v244
	v_sub_f32_e32 v35, v85, v244
	v_exp_f32_e32 v34, v34
	v_exp_f32_e32 v35, v35
	v_cvt_pk_bf16_f32 v106, v82, v83
	s_waitcnt lgkmcnt(5)
	v_mfma_f32_32x32x16_bf16 v[18:33], v[178:181], v[38:41], v[18:33]
	v_sub_f32_e32 v36, v86, v244
	v_sub_f32_e32 v37, v87, v244
	v_exp_f32_e32 v36, v36
	v_exp_f32_e32 v37, v37
	v_cvt_pk_bf16_f32 v107, v34, v35
	s_waitcnt lgkmcnt(4)
	v_mfma_f32_32x32x16_bf16 v[2:17], v[166:169], v[38:41], v[2:17]
	v_sub_f32_e32 v38, v88, v244
	v_sub_f32_e32 v39, v89, v244
	v_exp_f32_e32 v38, v38
	v_exp_f32_e32 v39, v39
	v_cvt_pk_bf16_f32 v108, v36, v37
	s_waitcnt lgkmcnt(3)
	v_mfma_f32_32x32x16_bf16 v[18:33], v[186:189], v[42:45], v[18:33]
	v_sub_f32_e32 v40, v90, v244
	v_sub_f32_e32 v41, v91, v244
	v_exp_f32_e32 v40, v40
	v_exp_f32_e32 v41, v41
	v_cvt_pk_bf16_f32 v109, v38, v39
	s_waitcnt lgkmcnt(2)
	v_mfma_f32_32x32x16_bf16 v[2:17], v[174:177], v[42:45], v[2:17]
	v_sub_f32_e32 v42, v92, v244
	v_sub_f32_e32 v43, v93, v244
	v_exp_f32_e32 v42, v42
	v_exp_f32_e32 v43, v43
	v_cvt_pk_bf16_f32 v110, v40, v41
	s_waitcnt lgkmcnt(1)
	v_mfma_f32_32x32x16_bf16 v[18:33], v[190:193], v[46:49], v[18:33]
	v_sub_f32_e32 v44, v94, v244
	v_sub_f32_e32 v45, v95, v244
	v_exp_f32_e32 v44, v44
	v_exp_f32_e32 v45, v45
	v_cvt_pk_bf16_f32 v111, v42, v43
	s_waitcnt lgkmcnt(0)
	v_mfma_f32_32x32x16_bf16 v[2:17], v[182:185], v[46:49], v[2:17]
	v_pk_add_f32 v[48:49], v[248:249], v[206:207]
	v_pk_add_f32 v[34:35], v[36:37], v[34:35]
	v_sub_f32_e32 v46, v96, v244
	v_pk_add_f32 v[48:49], v[246:247], v[48:49]
	v_pk_add_f32 v[34:35], v[38:39], v[34:35]
	v_sub_f32_e32 v47, v97, v244
	v_pk_add_f32 v[48:49], v[112:113], v[48:49]
	v_exp_f32_e32 v46, v46
	v_pk_add_f32 v[34:35], v[40:41], v[34:35]
	v_exp_f32_e32 v47, v47
	v_pk_add_f32 v[48:49], v[82:83], v[48:49]
	v_cvt_pk_bf16_f32 v112, v44, v45
	v_pk_add_f32 v[34:35], v[42:43], v[34:35]
	v_pk_add_f32 v[48:49], v[44:45], v[48:49]
	v_pk_add_f32 v[34:35], v[46:47], v[34:35]
	v_cvt_pk_bf16_f32 v113, v46, v47
	v_pk_add_f32 v[206:207], v[48:49], v[34:35]
	v_mov_b64_e32 v[34:35], v[98:99]
	v_mov_b64_e32 v[36:37], v[100:101]
	v_mov_b64_e32 v[38:39], v[102:103]
	v_mov_b64_e32 v[40:41], v[104:105]
	v_mov_b64_e32 v[42:43], v[106:107]
	v_mov_b64_e32 v[44:45], v[108:109]
	v_mov_b64_e32 v[46:47], v[110:111]
	v_mov_b64_e32 v[48:49], v[112:113]

; __device__ __forceinline__ unsigned cvtpk(float lo, float hi) { const f32x2 v = {lo, hi}; const bf16x2_t b = __builtin_convertvector(v, bf16x2_t); return __builtin_bit_cast(unsigned, b); }
; #define MFMA32(a, b, c) __builtin_amdgcn_mfma_f32_32x32x16_bf16((a), (b), (c), 0, 0, 0)
; #define PV_IDX(g) (((g) & 1) * 4 + PV_KS(g))
; template <int DQK, int DV, bool MLA>
; __device__ __forceinline__ void attn_pass(LAS unsigned char* lds, const bf16_t* Qrow, const bf16_t* K0, int pitchK, const bf16_t* KrB, const bf16_t* Vt0, int NT, int q0w,
;                                           f32x16 (&o)[DV / 32], float& l_out, int tid) {
;     ...
;             if (pend) {
; #pragma unroll
;                 for (int g = 0; g <= NG; ++g) {
;                     if (g < NG) {
;                         o[PV_D(g)] = MFMA32(vf[PV_IDX(g)], pf[PV_KS(g)], o[PV_D(g)]);
;                         if (NDV == 4 && g < 8) vf[PV_IDX(g)] = VFRAG(vp, PV_D(g) + 2, PV_KS(g));
; #pragma unroll
;                         for (int e = g * EPG; e < (g + 1) * EPG; ++e) { if (e < 16) s0[e] = __builtin_amdgcn_exp2f(MLA ? s0[e] : s0[e] - m); else s1[e - 16] = __builtin_amdgcn_exp2f(MLA ? s1[e - 16] : s1[e - 16] - m); }
;                     }
;                     if (g > 0) {
; #pragma unroll
;                         for (int e = (g - 1) * EPG; e < g * EPG; ++e) {
;                             const float v = e < 16 ? s0[e] : s1[e - 16];
;                             if (e & 1) ps1 += v; else ps += v;
;                             if (e & 1) { const int j = e >> 1; pw[j >> 2][j & 3] = e < 16 ? cvtpk(s0[e - 1], s0[e]) : cvtpk(s1[e - 17], s1[e - 16]); }
;                         }
;                     }
;                     __builtin_amdgcn_sched_barrier(0);
;                 }
.LBB0_159:
	s_or_saveexec_b64 s[6:7], s[6:7]
	v_mov_b32_e32 v205, 0
	s_xor_b64 exec, exec, s[6:7]
	s_cbranch_execz .LBB0_161
	s_waitcnt lgkmcnt(7)
	v_mfma_f32_32x32x16_bf16 v[66:81], v[170:173], v[50:53], v[66:81]
	v_sub_f32_e32 v98, v98, v207
	ds_read_b128 v[170:173], v221 offset:40960
	v_exp_f32_e32 v204, v98
	v_sub_f32_e32 v98, v99, v207
	v_exp_f32_e32 v205, v98
	s_waitcnt lgkmcnt(7)
	v_mfma_f32_32x32x16_bf16 v[34:49], v[162:165], v[50:53], v[34:49]
	ds_read_b128 v[162:165], v221 offset:45056
	v_sub_f32_e32 v98, v100, v207
	v_exp_f32_e32 v240, v98
	v_sub_f32_e32 v98, v101, v207
	v_exp_f32_e32 v241, v98
	v_cvt_pk_bf16_f32 v98, v204, v205
	s_waitcnt lgkmcnt(7)
	v_mfma_f32_32x32x16_bf16 v[66:81], v[178:181], v[54:57], v[66:81]
	ds_read_b128 v[178:181], v215 offset:40960
	v_sub_f32_e32 v99, v102, v207
	v_exp_f32_e32 v102, v99
	v_sub_f32_e32 v99, v103, v207
	v_exp_f32_e32 v103, v99
	v_cvt_pk_bf16_f32 v99, v240, v241
	s_waitcnt lgkmcnt(7)
	v_mfma_f32_32x32x16_bf16 v[34:49], v[166:169], v[54:57], v[34:49]
	ds_read_b128 v[166:169], v215 offset:45056
	v_sub_f32_e32 v100, v104, v207
	v_exp_f32_e32 v104, v100
	v_sub_f32_e32 v100, v105, v207
	v_exp_f32_e32 v105, v100
	v_cvt_pk_bf16_f32 v100, v102, v103
	s_waitcnt lgkmcnt(7)
	v_mfma_f32_32x32x16_bf16 v[66:81], v[186:189], v[58:61], v[66:81]
	ds_read_b128 v[186:189], v214 offset:40960
	v_sub_f32_e32 v101, v106, v207
	v_exp_f32_e32 v106, v101
	v_sub_f32_e32 v101, v107, v207
	v_exp_f32_e32 v107, v101
	v_cvt_pk_bf16_f32 v101, v104, v105
	s_waitcnt lgkmcnt(7)
	v_mfma_f32_32x32x16_bf16 v[34:49], v[174:177], v[58:61], v[34:49]
	v_pk_add_f32 v[102:103], v[104:105], v[102:103]
	v_sub_f32_e32 v108, v108, v207
	ds_read_b128 v[174:177], v214 offset:45056
	v_exp_f32_e32 v214, v108
	v_sub_f32_e32 v108, v109, v207
	v_exp_f32_e32 v215, v108
	v_pk_add_f32 v[102:103], v[106:107], v[102:103]
	v_pk_add_f32 v[108:109], v[240:241], v[204:205]
	s_nop 0
	v_pk_add_f32 v[204:205], v[102:103], v[108:109]
	v_cvt_pk_bf16_f32 v102, v106, v107
	s_waitcnt lgkmcnt(7)
	v_mfma_f32_32x32x16_bf16 v[66:81], v[190:193], v[62:65], v[66:81]
	ds_read_b128 v[190:193], v213 offset:40960
	v_sub_f32_e32 v103, v110, v207
	v_exp_f32_e32 v240, v103
	v_sub_f32_e32 v103, v111, v207
	v_exp_f32_e32 v241, v103
	v_cvt_pk_bf16_f32 v103, v214, v215
	s_waitcnt lgkmcnt(7)
	v_mfma_f32_32x32x16_bf16 v[34:49], v[182:185], v[62:65], v[34:49]
	ds_read_b128 v[182:185], v213 offset:45056
	v_sub_f32_e32 v104, v112, v207
	v_exp_f32_e32 v112, v104
	v_sub_f32_e32 v104, v113, v207
	v_exp_f32_e32 v113, v104
	v_cvt_pk_bf16_f32 v104, v240, v241
	s_waitcnt lgkmcnt(7)
	v_mfma_f32_32x32x16_bf16 v[18:33], v[170:173], v[50:53], v[18:33]
	v_sub_f32_e32 v82, v82, v207
	v_sub_f32_e32 v83, v83, v207
	v_exp_f32_e32 v82, v82
	v_exp_f32_e32 v83, v83
	v_cvt_pk_bf16_f32 v105, v112, v113
	s_waitcnt lgkmcnt(6)
	v_mfma_f32_32x32x16_bf16 v[2:17], v[162:165], v[50:53], v[2:17]
	v_sub_f32_e32 v50, v84, v207
	v_sub_f32_e32 v51, v85, v207
	v_exp_f32_e32 v50, v50
	v_exp_f32_e32 v51, v51
	v_cvt_pk_bf16_f32 v106, v82, v83
	s_waitcnt lgkmcnt(5)
	v_mfma_f32_32x32x16_bf16 v[18:33], v[178:181], v[54:57], v[18:33]
	v_sub_f32_e32 v52, v86, v207
	v_sub_f32_e32 v53, v87, v207
	v_exp_f32_e32 v52, v52
	v_exp_f32_e32 v53, v53
	v_cvt_pk_bf16_f32 v107, v50, v51
	s_waitcnt lgkmcnt(4)
	v_mfma_f32_32x32x16_bf16 v[2:17], v[166:169], v[54:57], v[2:17]
	v_sub_f32_e32 v54, v88, v207
	v_sub_f32_e32 v55, v89, v207
	v_exp_f32_e32 v54, v54
	v_exp_f32_e32 v55, v55
	v_cvt_pk_bf16_f32 v108, v52, v53
	s_waitcnt lgkmcnt(3)
	v_mfma_f32_32x32x16_bf16 v[18:33], v[186:189], v[58:61], v[18:33]
	v_sub_f32_e32 v56, v90, v207
	v_sub_f32_e32 v57, v91, v207
	v_exp_f32_e32 v56, v56
	v_exp_f32_e32 v57, v57
	v_cvt_pk_bf16_f32 v109, v54, v55
	s_waitcnt lgkmcnt(2)
	v_mfma_f32_32x32x16_bf16 v[2:17], v[174:177], v[58:61], v[2:17]
	v_sub_f32_e32 v58, v92, v207
	v_sub_f32_e32 v59, v93, v207
	v_exp_f32_e32 v58, v58
	v_exp_f32_e32 v59, v59
	v_cvt_pk_bf16_f32 v110, v56, v57
	s_waitcnt lgkmcnt(1)
	v_mfma_f32_32x32x16_bf16 v[18:33], v[190:193], v[62:65], v[18:33]
	v_sub_f32_e32 v60, v94, v207
	v_sub_f32_e32 v61, v95, v207
	v_exp_f32_e32 v60, v60
	v_exp_f32_e32 v61, v61
	v_cvt_pk_bf16_f32 v111, v58, v59
	s_waitcnt lgkmcnt(0)
	v_mfma_f32_32x32x16_bf16 v[2:17], v[182:185], v[62:65], v[2:17]
	v_pk_add_f32 v[64:65], v[214:215], v[204:205]
	v_pk_add_f32 v[50:51], v[52:53], v[50:51]
	v_sub_f32_e32 v62, v96, v207
	v_pk_add_f32 v[64:65], v[240:241], v[64:65]
	v_pk_add_f32 v[50:51], v[54:55], v[50:51]
	v_sub_f32_e32 v63, v97, v207
	v_pk_add_f32 v[64:65], v[112:113], v[64:65]
	v_exp_f32_e32 v62, v62
	v_pk_add_f32 v[50:51], v[56:57], v[50:51]
	v_exp_f32_e32 v63, v63
	v_pk_add_f32 v[64:65], v[82:83], v[64:65]
	v_cvt_pk_bf16_f32 v112, v60, v61
	v_pk_add_f32 v[50:51], v[58:59], v[50:51]
	v_pk_add_f32 v[64:65], v[60:61], v[64:65]
	v_pk_add_f32 v[50:51], v[62:63], v[50:51]
	v_cvt_pk_bf16_f32 v113, v62, v63
	v_pk_add_f32 v[204:205], v[64:65], v[50:51]
	v_mov_b64_e32 v[50:51], v[98:99]
	v_mov_b64_e32 v[52:53], v[100:101]
	v_mov_b64_e32 v[54:55], v[102:103]
	v_mov_b64_e32 v[56:57], v[104:105]
	v_mov_b64_e32 v[58:59], v[106:107]
	v_mov_b64_e32 v[60:61], v[108:109]
	v_mov_b64_e32 v[62:63], v[110:111]
	v_mov_b64_e32 v[64:65], v[112:113]
